# HGRN finalize loop hand-written: rows fetched three ahead into a four-set register ring, one counted wait per row (on top of version 87)
# speedup vs baseline: 1.0173x; 1.0054x over previous
.LBB0_501:
	s_or_b64 exec, exec, s[8:9]
	v_mov_b32_e32 v8, v200
	s_add_u32 s8, s26, 0x2d000000
	v_lshlrev_b32_e32 v0, 3, v8
	v_and_b32_e32 v9, 0x1f8, v0
	v_lshlrev_b32_e32 v4, 2, v9
	global_load_dwordx4 v[0:3], v4, s[10:11] offset:16
	s_nop 0
	global_load_dwordx4 v[4:7], v4, s[10:11]
	s_addc_u32 s9, s27, 0
	s_add_u32 s12, s26, 0x35000000
	s_addc_u32 s13, s27, 0
	s_add_u32 s10, s26, 0x25000000
	s_addc_u32 s11, s27, 0
	s_abs_i32 s1, s72
	v_readfirstlane_b32 s0, v8
	v_cvt_f32_u32_e32 v8, s1
	s_ashr_i32 s7, s0, 6
	s_add_i32 s14, s7, s73
	s_sub_i32 s17, 0, s1
	v_rcp_iflag_f32_e32 v8, v8
	s_sub_i32 s0, s72, s14
	s_add_i32 s0, s0, 0xffff
	s_xor_b32 s6, s0, s72
	v_mul_f32_e32 v8, 0x4f7ffffe, v8
	v_cvt_u32_f32_e32 v8, v8
	s_abs_i32 s0, s0
	s_ashr_i32 s6, s6, 31
	s_mov_b32 s15, 0
	v_readfirstlane_b32 s18, v8
	s_mul_i32 s17, s17, s18
	s_mul_hi_u32 s17, s18, s17
	s_add_i32 s18, s18, s17
	s_mul_hi_u32 s17, s0, s18
	s_mul_i32 s18, s17, s1
	s_sub_i32 s0, s0, s18
	s_add_i32 s18, s17, 1
	s_sub_i32 s19, s0, s1
	s_cmp_ge_u32 s0, s1
	s_cselect_b32 s17, s18, s17
	s_cselect_b32 s0, s19, s0
	s_add_i32 s18, s17, 1
	s_cmp_ge_u32 s0, s1
	s_cselect_b32 s0, s18, s17
	s_xor_b32 s0, s0, s6
	s_sub_i32 s6, s0, s6
	v_mov_b32_e32 v145, 0
	s_cmp_gt_i32 s6, 3
	v_lshlrev_b32_e32 v144, 1, v9
	s_cbranch_scc0 .LBB0_509
	s_cmp_eq_u32 s96, 0x100
	s_cbranch_scc1 .Lfin_hand
	s_ashr_i32 s15, s14, 31
	s_lshl_b64 s[0:1], s[14:15], 10
	s_add_u32 s18, s8, s0
	s_addc_u32 s19, s9, s1
	s_add_u32 s0, s12, s0
	s_addc_u32 s1, s13, s1
	global_load_dwordx4 v[8:11], v144, s[18:19]
	global_load_dwordx4 v[12:15], v144, s[0:1]
	s_mul_i32 s0, s14, 0x1c00
	s_mul_hi_i32 s1, s14, 0x1c00
	s_add_u32 s0, s92, s0
	s_addc_u32 s1, s93, s1
	v_lshl_add_u64 v[16:17], s[0:1], 0, v[144:145]
	s_add_i32 s0, s14, s72
	s_ashr_i32 s1, s0, 31
	s_lshl_b64 s[18:19], s[0:1], 10
	s_add_u32 s30, s8, s18
	s_addc_u32 s31, s9, s19
	s_movk_i32 s15, 0x1000
	s_add_u32 s18, s12, s18
	v_add_co_u32_e32 v24, vcc, s15, v16
	s_addc_u32 s19, s13, s19
	s_mul_i32 s17, s0, 0x1c00
	v_addc_co_u32_e32 v25, vcc, 0, v17, vcc
	global_load_dwordx4 v[16:19], v144, s[30:31]
	global_load_dwordx4 v[20:23], v144, s[18:19]
	s_mul_hi_i32 s1, s0, 0x1c00
	s_add_u32 s18, s92, s17
	s_addc_u32 s19, s93, s1
	s_add_i32 s0, s0, s72
	s_ashr_i32 s1, s0, 31
	v_lshl_add_u64 v[26:27], s[18:19], 0, v[144:145]
	s_lshl_b64 s[18:19], s[0:1], 10
	s_add_u32 s30, s8, s18
	s_addc_u32 s31, s9, s19
	s_add_u32 s18, s12, s18
	v_add_co_u32_e32 v26, vcc, s15, v26
	s_addc_u32 s19, s13, s19
	s_mul_i32 s17, s0, 0x1c00
	v_addc_co_u32_e32 v27, vcc, 0, v27, vcc
	global_load_dwordx4 v[28:31], v[24:25], off
	global_load_dwordx4 v[32:35], v[26:27], off
	global_load_dwordx4 v[36:39], v144, s[30:31]
	global_load_dwordx4 v[40:43], v144, s[18:19]
	s_mul_hi_i32 s1, s0, 0x1c00
	s_add_u32 s18, s92, s17
	s_addc_u32 s19, s93, s1
	s_add_i32 s0, s0, s72
	s_ashr_i32 s1, s0, 31
	v_lshl_add_u64 v[24:25], s[18:19], 0, v[144:145]
	s_lshl_b64 s[18:19], s[0:1], 10
	s_add_u32 s30, s8, s18
	s_addc_u32 s31, s9, s19
	s_add_u32 s18, s12, s18
	s_addc_u32 s19, s13, s19
	s_mul_hi_i32 s1, s0, 0x1c00
	s_mulk_i32 s0, 0x1c00
	s_add_u32 s0, s92, s0
	v_add_co_u32_e32 v24, vcc, s15, v24
	s_addc_u32 s1, s93, s1
	s_nop 0
	v_addc_co_u32_e32 v25, vcc, 0, v25, vcc
	v_lshl_add_u64 v[26:27], s[0:1], 0, v[144:145]
	v_add_co_u32_e32 v26, vcc, 0x1000, v26
	global_load_dwordx4 v[44:47], v144, s[30:31]
	global_load_dwordx4 v[48:51], v144, s[18:19]
	v_addc_co_u32_e32 v27, vcc, 0, v27, vcc
	global_load_dwordx4 v[52:55], v[24:25], off
	global_load_dwordx4 v[56:59], v[26:27], off
	s_cmp_gt_u32 s6, 7
	s_cbranch_scc0 .LBB0_506
	v_mov_b32_e32 v145, 0
	s_waitcnt vmcnt(0)
	v_mov_b64_e32 v[94:95], v[58:59]
	v_mov_b64_e32 v[98:99], v[50:51]
	v_mov_b64_e32 v[102:103], v[46:47]
	v_mov_b64_e32 v[82:83], v[54:55]
	v_mov_b64_e32 v[86:87], v[42:43]
	v_mov_b64_e32 v[90:91], v[38:39]
	v_mov_b64_e32 v[70:71], v[34:35]
	v_mov_b64_e32 v[74:75], v[22:23]
	v_mov_b64_e32 v[78:79], v[18:19]
	v_mov_b64_e32 v[24:25], v[28:29]
	v_mov_b64_e32 v[62:63], v[14:15]
	v_mov_b64_e32 v[142:143], v[10:11]
	v_lshl_add_u64 v[154:155], s[8:9], 0, v[144:145]
	v_lshl_add_u64 v[156:157], s[12:13], 0, v[144:145]
	v_lshl_add_u64 v[158:159], s[10:11], 0, v[144:145]
	v_mov_b32_e32 v152, v4
	v_mov_b32_e32 v153, v6
	v_mov_b32_e32 v150, v5
	v_mov_b32_e32 v151, v7
	v_mov_b32_e32 v148, v0
	v_mov_b32_e32 v149, v2
	v_mov_b32_e32 v146, v1
	v_mov_b32_e32 v147, v3
	s_lshl_b32 s40, s72, 2
	s_lshl_b32 s41, s96, 4
	s_mov_b32 s42, 8
	s_mov_b32 s43, 0xffff0000
	v_mov_b32_e32 v168, 0x358637bd
	s_mov_b32 s44, 0xf800000
	v_mov_b32_e32 v169, 0x260
	s_movk_i32 s45, 0x7fff
	s_mov_b32 s18, s14
	v_mov_b64_e32 v[92:93], v[56:57]
	v_mov_b64_e32 v[96:97], v[48:49]
	v_mov_b64_e32 v[100:101], v[44:45]
	v_mov_b64_e32 v[80:81], v[52:53]
	v_mov_b64_e32 v[84:85], v[40:41]
	v_mov_b64_e32 v[88:89], v[36:37]
	v_mov_b64_e32 v[68:69], v[32:33]
	v_mov_b64_e32 v[72:73], v[20:21]
	v_mov_b64_e32 v[76:77], v[16:17]
	v_mov_b64_e32 v[26:27], v[30:31]
	v_mov_b64_e32 v[60:61], v[12:13]
	v_mov_b64_e32 v[140:141], v[8:9]

.Lfin_hand:
	s_lshl_b32 s0, s14, 10
	s_mov_b32 s1, 0
	v_mov_b32_e32 v90, s0
	v_add_u32_e32 v90, v90, v144
	v_mov_b32_e32 v91, 0
	v_lshl_add_u64 v[64:65], s[8:9], 0, v[90:91]
	v_lshl_add_u64 v[66:67], s[12:13], 0, v[90:91]
	s_mul_i32 s0, s14, 0x1c00
	s_add_u32 s0, s0, 0x1000
	v_mov_b32_e32 v90, s0
	v_add_u32_e32 v90, v90, v144
	v_lshl_add_u64 v[68:69], s[92:93], 0, v[90:91]
	s_lshl_b32 s0, s14, 11
	v_mov_b32_e32 v90, s0
	v_add_u32_e32 v90, v90, v144
	v_lshl_add_u64 v[70:71], s[10:11], 0, v[90:91]
	global_load_dwordx4 v[16:19], v[64:65], off
	global_load_dwordx4 v[20:23], v[66:67], off
	global_load_dwordx4 v[24:27], v[68:69], off
	s_mov_b32 s0, 0x200000
	s_mov_b32 s6, 0xe00000
	s_mov_b32 s1, 0
	s_mov_b32 s7, 0
	v_lshl_add_u64 v[64:65], v[64:65], 0, s[0:1]
	v_lshl_add_u64 v[66:67], v[66:67], 0, s[0:1]
	v_lshl_add_u64 v[68:69], v[68:69], 0, s[6:7]
	global_load_dwordx4 v[28:31], v[64:65], off
	global_load_dwordx4 v[32:35], v[66:67], off
	global_load_dwordx4 v[36:39], v[68:69], off
	s_mov_b32 s0, 0x200000
	s_mov_b32 s6, 0xe00000
	s_mov_b32 s1, 0
	s_mov_b32 s7, 0
	v_lshl_add_u64 v[64:65], v[64:65], 0, s[0:1]
	v_lshl_add_u64 v[66:67], v[66:67], 0, s[0:1]
	v_lshl_add_u64 v[68:69], v[68:69], 0, s[6:7]
	global_load_dwordx4 v[40:43], v[64:65], off
	global_load_dwordx4 v[44:47], v[66:67], off
	global_load_dwordx4 v[48:51], v[68:69], off
	s_mov_b32 s0, 0x200000
	s_mov_b32 s6, 0xe00000
	s_mov_b32 s1, 0
	s_mov_b32 s7, 0
	v_lshl_add_u64 v[64:65], v[64:65], 0, s[0:1]
	v_lshl_add_u64 v[66:67], v[66:67], 0, s[0:1]
	v_lshl_add_u64 v[68:69], v[68:69], 0, s[6:7]
	s_waitcnt vmcnt(0)
	s_mov_b32 s30, 0
.Lfin_loop:
	global_load_dwordx4 v[52:55], v[64:65], off
	global_load_dwordx4 v[56:59], v[66:67], off
	global_load_dwordx4 v[60:63], v[68:69], off
	s_cmp_lt_u32 s30, 28
	s_cselect_b32 s0, 0x200000, 0
	s_cselect_b32 s6, 0xe00000, 0
	s_mov_b32 s1, 0
	s_mov_b32 s7, 0
	v_lshl_add_u64 v[64:65], v[64:65], 0, s[0:1]
	v_lshl_add_u64 v[66:67], v[66:67], 0, s[0:1]
	v_lshl_add_u64 v[68:69], v[68:69], 0, s[6:7]
	s_waitcnt vmcnt(12)
	v_lshlrev_b32_e32 v72, 16, v16
	v_and_b32_e32 v73, 0xffff0000, v16
	v_lshlrev_b32_e32 v88, 16, v20
	v_and_b32_e32 v89, 0xffff0000, v20
	v_add_f32_e32 v72, v72, v88
	v_add_f32_e32 v73, v73, v89
	v_lshlrev_b32_e32 v74, 16, v17
	v_and_b32_e32 v75, 0xffff0000, v17
	v_lshlrev_b32_e32 v88, 16, v21
	v_and_b32_e32 v89, 0xffff0000, v21
	v_add_f32_e32 v74, v74, v88
	v_add_f32_e32 v75, v75, v89
	v_lshlrev_b32_e32 v76, 16, v18
	v_and_b32_e32 v77, 0xffff0000, v18
	v_lshlrev_b32_e32 v88, 16, v22
	v_and_b32_e32 v89, 0xffff0000, v22
	v_add_f32_e32 v76, v76, v88
	v_add_f32_e32 v77, v77, v89
	v_lshlrev_b32_e32 v78, 16, v19
	v_and_b32_e32 v79, 0xffff0000, v19
	v_lshlrev_b32_e32 v88, 16, v23
	v_and_b32_e32 v89, 0xffff0000, v23
	v_add_f32_e32 v78, v78, v88
	v_add_f32_e32 v79, v79, v89
	v_mul_f32_e32 v80, v72, v72
	v_fmac_f32_e32 v80, v73, v73
	v_fmac_f32_e32 v80, v74, v74
	v_fmac_f32_e32 v80, v75, v75
	v_fmac_f32_e32 v80, v76, v76
	v_fmac_f32_e32 v80, v77, v77
	v_fmac_f32_e32 v80, v78, v78
	v_fmac_f32_e32 v80, v79, v79
	s_nop 1
	v_add_f32_dpp v81, v80, v80 quad_perm:[1,0,3,2] row_mask:0xf bank_mask:0xf
	s_nop 1
	v_add_f32_dpp v81, v81, v81 quad_perm:[2,3,0,1] row_mask:0xf bank_mask:0xf
	s_nop 1
	v_add_f32_dpp v81, v81, v81 row_half_mirror row_mask:0xf bank_mask:0xf
	s_nop 1
	v_add_f32_dpp v81, v81, v81 row_mirror row_mask:0xf bank_mask:0xf
	v_mov_b32_e32 v82, 0x3c000000
	v_mov_b32_e32 v83, 0x358637bd
	v_fma_f32 v81, v81, v82, v83
	v_rsq_f32_e32 v81, v81
	s_nop 0
	v_mul_f32_e32 v72, v72, v81
	v_mul_f32_e32 v72, v72, v4
	v_mul_f32_e32 v73, v73, v81
	v_mul_f32_e32 v73, v73, v5
	v_mul_f32_e32 v74, v74, v81
	v_mul_f32_e32 v74, v74, v6
	v_mul_f32_e32 v75, v75, v81
	v_mul_f32_e32 v75, v75, v7
	v_mul_f32_e32 v76, v76, v81
	v_mul_f32_e32 v76, v76, v0
	v_mul_f32_e32 v77, v77, v81
	v_mul_f32_e32 v77, v77, v1
	v_mul_f32_e32 v78, v78, v81
	v_mul_f32_e32 v78, v78, v2
	v_mul_f32_e32 v79, v79, v81
	v_mul_f32_e32 v79, v79, v3
	v_lshlrev_b32_e32 v88, 16, v24
	v_and_b32_e32 v89, 0xffff0000, v24
	v_mul_f32_e32 v72, v72, v88
	v_mul_f32_e32 v73, v73, v89
	v_cvt_pk_bf16_f32 v84, v72, v73
	v_lshlrev_b32_e32 v88, 16, v25
	v_and_b32_e32 v89, 0xffff0000, v25
	v_mul_f32_e32 v74, v74, v88
	v_mul_f32_e32 v75, v75, v89
	v_cvt_pk_bf16_f32 v85, v74, v75
	v_lshlrev_b32_e32 v88, 16, v26
	v_and_b32_e32 v89, 0xffff0000, v26
	v_mul_f32_e32 v76, v76, v88
	v_mul_f32_e32 v77, v77, v89
	v_cvt_pk_bf16_f32 v86, v76, v77
	v_lshlrev_b32_e32 v88, 16, v27
	v_and_b32_e32 v89, 0xffff0000, v27
	v_mul_f32_e32 v78, v78, v88
	v_mul_f32_e32 v79, v79, v89
	v_cvt_pk_bf16_f32 v87, v78, v79
	global_store_dwordx4 v[70:71], v[84:87], off
	s_mov_b32 s18, 0x400000
	s_mov_b32 s19, 0
	v_lshl_add_u64 v[70:71], v[70:71], 0, s[18:19]
	s_add_u32 s30, s30, 1
	global_load_dwordx4 v[16:19], v[64:65], off
	global_load_dwordx4 v[20:23], v[66:67], off
	global_load_dwordx4 v[24:27], v[68:69], off
	s_cmp_lt_u32 s30, 28
	s_cselect_b32 s0, 0x200000, 0
	s_cselect_b32 s6, 0xe00000, 0
	s_mov_b32 s1, 0
	s_mov_b32 s7, 0
	v_lshl_add_u64 v[64:65], v[64:65], 0, s[0:1]
	v_lshl_add_u64 v[66:67], v[66:67], 0, s[0:1]
	v_lshl_add_u64 v[68:69], v[68:69], 0, s[6:7]
	s_waitcnt vmcnt(12)
	v_lshlrev_b32_e32 v72, 16, v28
	v_and_b32_e32 v73, 0xffff0000, v28
	v_lshlrev_b32_e32 v88, 16, v32
	v_and_b32_e32 v89, 0xffff0000, v32
	v_add_f32_e32 v72, v72, v88
	v_add_f32_e32 v73, v73, v89
	v_lshlrev_b32_e32 v74, 16, v29
	v_and_b32_e32 v75, 0xffff0000, v29
	v_lshlrev_b32_e32 v88, 16, v33
	v_and_b32_e32 v89, 0xffff0000, v33
	v_add_f32_e32 v74, v74, v88
	v_add_f32_e32 v75, v75, v89
	v_lshlrev_b32_e32 v76, 16, v30
	v_and_b32_e32 v77, 0xffff0000, v30
	v_lshlrev_b32_e32 v88, 16, v34
	v_and_b32_e32 v89, 0xffff0000, v34
	v_add_f32_e32 v76, v76, v88
	v_add_f32_e32 v77, v77, v89
	v_lshlrev_b32_e32 v78, 16, v31
	v_and_b32_e32 v79, 0xffff0000, v31
	v_lshlrev_b32_e32 v88, 16, v35
	v_and_b32_e32 v89, 0xffff0000, v35
	v_add_f32_e32 v78, v78, v88
	v_add_f32_e32 v79, v79, v89
	v_mul_f32_e32 v80, v72, v72
	v_fmac_f32_e32 v80, v73, v73
	v_fmac_f32_e32 v80, v74, v74
	v_fmac_f32_e32 v80, v75, v75
	v_fmac_f32_e32 v80, v76, v76
	v_fmac_f32_e32 v80, v77, v77
	v_fmac_f32_e32 v80, v78, v78
	v_fmac_f32_e32 v80, v79, v79
	s_nop 1
	v_add_f32_dpp v81, v80, v80 quad_perm:[1,0,3,2] row_mask:0xf bank_mask:0xf
	s_nop 1
	v_add_f32_dpp v81, v81, v81 quad_perm:[2,3,0,1] row_mask:0xf bank_mask:0xf
	s_nop 1
	v_add_f32_dpp v81, v81, v81 row_half_mirror row_mask:0xf bank_mask:0xf
	s_nop 1
	v_add_f32_dpp v81, v81, v81 row_mirror row_mask:0xf bank_mask:0xf
	v_mov_b32_e32 v82, 0x3c000000
	v_mov_b32_e32 v83, 0x358637bd
	v_fma_f32 v81, v81, v82, v83
	v_rsq_f32_e32 v81, v81
	s_nop 0
	v_mul_f32_e32 v72, v72, v81
	v_mul_f32_e32 v72, v72, v4
	v_mul_f32_e32 v73, v73, v81
	v_mul_f32_e32 v73, v73, v5
	v_mul_f32_e32 v74, v74, v81
	v_mul_f32_e32 v74, v74, v6
	v_mul_f32_e32 v75, v75, v81
	v_mul_f32_e32 v75, v75, v7
	v_mul_f32_e32 v76, v76, v81
	v_mul_f32_e32 v76, v76, v0
	v_mul_f32_e32 v77, v77, v81
	v_mul_f32_e32 v77, v77, v1
	v_mul_f32_e32 v78, v78, v81
	v_mul_f32_e32 v78, v78, v2
	v_mul_f32_e32 v79, v79, v81
	v_mul_f32_e32 v79, v79, v3
	v_lshlrev_b32_e32 v88, 16, v36
	v_and_b32_e32 v89, 0xffff0000, v36
	v_mul_f32_e32 v72, v72, v88
	v_mul_f32_e32 v73, v73, v89
	v_cvt_pk_bf16_f32 v84, v72, v73
	v_lshlrev_b32_e32 v88, 16, v37
	v_and_b32_e32 v89, 0xffff0000, v37
	v_mul_f32_e32 v74, v74, v88
	v_mul_f32_e32 v75, v75, v89
	v_cvt_pk_bf16_f32 v85, v74, v75
	v_lshlrev_b32_e32 v88, 16, v38
	v_and_b32_e32 v89, 0xffff0000, v38
	v_mul_f32_e32 v76, v76, v88
	v_mul_f32_e32 v77, v77, v89
	v_cvt_pk_bf16_f32 v86, v76, v77
	v_lshlrev_b32_e32 v88, 16, v39
	v_and_b32_e32 v89, 0xffff0000, v39
	v_mul_f32_e32 v78, v78, v88
	v_mul_f32_e32 v79, v79, v89
	v_cvt_pk_bf16_f32 v87, v78, v79
	global_store_dwordx4 v[70:71], v[84:87], off
	s_mov_b32 s18, 0x400000
	s_mov_b32 s19, 0
	v_lshl_add_u64 v[70:71], v[70:71], 0, s[18:19]
	s_add_u32 s30, s30, 1
	global_load_dwordx4 v[28:31], v[64:65], off
	global_load_dwordx4 v[32:35], v[66:67], off
	global_load_dwordx4 v[36:39], v[68:69], off
	s_cmp_lt_u32 s30, 28
	s_cselect_b32 s0, 0x200000, 0
	s_cselect_b32 s6, 0xe00000, 0
	s_mov_b32 s1, 0
	s_mov_b32 s7, 0
	v_lshl_add_u64 v[64:65], v[64:65], 0, s[0:1]
	v_lshl_add_u64 v[66:67], v[66:67], 0, s[0:1]
	v_lshl_add_u64 v[68:69], v[68:69], 0, s[6:7]
	s_waitcnt vmcnt(12)
	v_lshlrev_b32_e32 v72, 16, v40
	v_and_b32_e32 v73, 0xffff0000, v40
	v_lshlrev_b32_e32 v88, 16, v44
	v_and_b32_e32 v89, 0xffff0000, v44
	v_add_f32_e32 v72, v72, v88
	v_add_f32_e32 v73, v73, v89
	v_lshlrev_b32_e32 v74, 16, v41
	v_and_b32_e32 v75, 0xffff0000, v41
	v_lshlrev_b32_e32 v88, 16, v45
	v_and_b32_e32 v89, 0xffff0000, v45
	v_add_f32_e32 v74, v74, v88
	v_add_f32_e32 v75, v75, v89
	v_lshlrev_b32_e32 v76, 16, v42
	v_and_b32_e32 v77, 0xffff0000, v42
	v_lshlrev_b32_e32 v88, 16, v46
	v_and_b32_e32 v89, 0xffff0000, v46
	v_add_f32_e32 v76, v76, v88
	v_add_f32_e32 v77, v77, v89
	v_lshlrev_b32_e32 v78, 16, v43
	v_and_b32_e32 v79, 0xffff0000, v43
	v_lshlrev_b32_e32 v88, 16, v47
	v_and_b32_e32 v89, 0xffff0000, v47
	v_add_f32_e32 v78, v78, v88
	v_add_f32_e32 v79, v79, v89
	v_mul_f32_e32 v80, v72, v72
	v_fmac_f32_e32 v80, v73, v73
	v_fmac_f32_e32 v80, v74, v74
	v_fmac_f32_e32 v80, v75, v75
	v_fmac_f32_e32 v80, v76, v76
	v_fmac_f32_e32 v80, v77, v77
	v_fmac_f32_e32 v80, v78, v78
	v_fmac_f32_e32 v80, v79, v79
	s_nop 1
	v_add_f32_dpp v81, v80, v80 quad_perm:[1,0,3,2] row_mask:0xf bank_mask:0xf
	s_nop 1
	v_add_f32_dpp v81, v81, v81 quad_perm:[2,3,0,1] row_mask:0xf bank_mask:0xf
	s_nop 1
	v_add_f32_dpp v81, v81, v81 row_half_mirror row_mask:0xf bank_mask:0xf
	s_nop 1
	v_add_f32_dpp v81, v81, v81 row_mirror row_mask:0xf bank_mask:0xf
	v_mov_b32_e32 v82, 0x3c000000
	v_mov_b32_e32 v83, 0x358637bd
	v_fma_f32 v81, v81, v82, v83
	v_rsq_f32_e32 v81, v81
	s_nop 0
	v_mul_f32_e32 v72, v72, v81
	v_mul_f32_e32 v72, v72, v4
	v_mul_f32_e32 v73, v73, v81
	v_mul_f32_e32 v73, v73, v5
	v_mul_f32_e32 v74, v74, v81
	v_mul_f32_e32 v74, v74, v6
	v_mul_f32_e32 v75, v75, v81
	v_mul_f32_e32 v75, v75, v7
	v_mul_f32_e32 v76, v76, v81
	v_mul_f32_e32 v76, v76, v0
	v_mul_f32_e32 v77, v77, v81
	v_mul_f32_e32 v77, v77, v1
	v_mul_f32_e32 v78, v78, v81
	v_mul_f32_e32 v78, v78, v2
	v_mul_f32_e32 v79, v79, v81
	v_mul_f32_e32 v79, v79, v3
	v_lshlrev_b32_e32 v88, 16, v48
	v_and_b32_e32 v89, 0xffff0000, v48
	v_mul_f32_e32 v72, v72, v88
	v_mul_f32_e32 v73, v73, v89
	v_cvt_pk_bf16_f32 v84, v72, v73
	v_lshlrev_b32_e32 v88, 16, v49
	v_and_b32_e32 v89, 0xffff0000, v49
	v_mul_f32_e32 v74, v74, v88
	v_mul_f32_e32 v75, v75, v89
	v_cvt_pk_bf16_f32 v85, v74, v75
	v_lshlrev_b32_e32 v88, 16, v50
	v_and_b32_e32 v89, 0xffff0000, v50
	v_mul_f32_e32 v76, v76, v88
	v_mul_f32_e32 v77, v77, v89
	v_cvt_pk_bf16_f32 v86, v76, v77
	v_lshlrev_b32_e32 v88, 16, v51
	v_and_b32_e32 v89, 0xffff0000, v51
	v_mul_f32_e32 v78, v78, v88
	v_mul_f32_e32 v79, v79, v89
	v_cvt_pk_bf16_f32 v87, v78, v79
	global_store_dwordx4 v[70:71], v[84:87], off
	s_mov_b32 s18, 0x400000
	s_mov_b32 s19, 0
	v_lshl_add_u64 v[70:71], v[70:71], 0, s[18:19]
	s_add_u32 s30, s30, 1
	global_load_dwordx4 v[40:43], v[64:65], off
	global_load_dwordx4 v[44:47], v[66:67], off
	global_load_dwordx4 v[48:51], v[68:69], off
	s_cmp_lt_u32 s30, 28
	s_cselect_b32 s0, 0x200000, 0
	s_cselect_b32 s6, 0xe00000, 0
	s_mov_b32 s1, 0
	s_mov_b32 s7, 0
	v_lshl_add_u64 v[64:65], v[64:65], 0, s[0:1]
	v_lshl_add_u64 v[66:67], v[66:67], 0, s[0:1]
	v_lshl_add_u64 v[68:69], v[68:69], 0, s[6:7]
	s_waitcnt vmcnt(12)
	v_lshlrev_b32_e32 v72, 16, v52
	v_and_b32_e32 v73, 0xffff0000, v52
	v_lshlrev_b32_e32 v88, 16, v56
	v_and_b32_e32 v89, 0xffff0000, v56
	v_add_f32_e32 v72, v72, v88
	v_add_f32_e32 v73, v73, v89
	v_lshlrev_b32_e32 v74, 16, v53
	v_and_b32_e32 v75, 0xffff0000, v53
	v_lshlrev_b32_e32 v88, 16, v57
	v_and_b32_e32 v89, 0xffff0000, v57
	v_add_f32_e32 v74, v74, v88
	v_add_f32_e32 v75, v75, v89
	v_lshlrev_b32_e32 v76, 16, v54
	v_and_b32_e32 v77, 0xffff0000, v54
	v_lshlrev_b32_e32 v88, 16, v58
	v_and_b32_e32 v89, 0xffff0000, v58
	v_add_f32_e32 v76, v76, v88
	v_add_f32_e32 v77, v77, v89
	v_lshlrev_b32_e32 v78, 16, v55
	v_and_b32_e32 v79, 0xffff0000, v55
	v_lshlrev_b32_e32 v88, 16, v59
	v_and_b32_e32 v89, 0xffff0000, v59
	v_add_f32_e32 v78, v78, v88
	v_add_f32_e32 v79, v79, v89
	v_mul_f32_e32 v80, v72, v72
	v_fmac_f32_e32 v80, v73, v73
	v_fmac_f32_e32 v80, v74, v74
	v_fmac_f32_e32 v80, v75, v75
	v_fmac_f32_e32 v80, v76, v76
	v_fmac_f32_e32 v80, v77, v77
	v_fmac_f32_e32 v80, v78, v78
	v_fmac_f32_e32 v80, v79, v79
	s_nop 1
	v_add_f32_dpp v81, v80, v80 quad_perm:[1,0,3,2] row_mask:0xf bank_mask:0xf
	s_nop 1
	v_add_f32_dpp v81, v81, v81 quad_perm:[2,3,0,1] row_mask:0xf bank_mask:0xf
	s_nop 1
	v_add_f32_dpp v81, v81, v81 row_half_mirror row_mask:0xf bank_mask:0xf
	s_nop 1
	v_add_f32_dpp v81, v81, v81 row_mirror row_mask:0xf bank_mask:0xf
	v_mov_b32_e32 v82, 0x3c000000
	v_mov_b32_e32 v83, 0x358637bd
	v_fma_f32 v81, v81, v82, v83
	v_rsq_f32_e32 v81, v81
	s_nop 0
	v_mul_f32_e32 v72, v72, v81
	v_mul_f32_e32 v72, v72, v4
	v_mul_f32_e32 v73, v73, v81
	v_mul_f32_e32 v73, v73, v5
	v_mul_f32_e32 v74, v74, v81
	v_mul_f32_e32 v74, v74, v6
	v_mul_f32_e32 v75, v75, v81
	v_mul_f32_e32 v75, v75, v7
	v_mul_f32_e32 v76, v76, v81
	v_mul_f32_e32 v76, v76, v0
	v_mul_f32_e32 v77, v77, v81
	v_mul_f32_e32 v77, v77, v1
	v_mul_f32_e32 v78, v78, v81
	v_mul_f32_e32 v78, v78, v2
	v_mul_f32_e32 v79, v79, v81
	v_mul_f32_e32 v79, v79, v3
	v_lshlrev_b32_e32 v88, 16, v60
	v_and_b32_e32 v89, 0xffff0000, v60
	v_mul_f32_e32 v72, v72, v88
	v_mul_f32_e32 v73, v73, v89
	v_cvt_pk_bf16_f32 v84, v72, v73
	v_lshlrev_b32_e32 v88, 16, v61
	v_and_b32_e32 v89, 0xffff0000, v61
	v_mul_f32_e32 v74, v74, v88
	v_mul_f32_e32 v75, v75, v89
	v_cvt_pk_bf16_f32 v85, v74, v75
	v_lshlrev_b32_e32 v88, 16, v62
	v_and_b32_e32 v89, 0xffff0000, v62
	v_mul_f32_e32 v76, v76, v88
	v_mul_f32_e32 v77, v77, v89
	v_cvt_pk_bf16_f32 v86, v76, v77
	v_lshlrev_b32_e32 v88, 16, v63
	v_and_b32_e32 v89, 0xffff0000, v63
	v_mul_f32_e32 v78, v78, v88
	v_mul_f32_e32 v79, v79, v89
	v_cvt_pk_bf16_f32 v87, v78, v79
	global_store_dwordx4 v[70:71], v[84:87], off
	s_mov_b32 s18, 0x400000
	s_mov_b32 s19, 0
	v_lshl_add_u64 v[70:71], v[70:71], 0, s[18:19]
	s_add_u32 s30, s30, 1
	s_cmp_lt_u32 s30, 32
	s_cbranch_scc1 .Lfin_loop
	s_branch .LBB0_512
